# residual epilogue rewritten: in-place FMA into accumulators, deeper load pipelining, lane permutation (ds_bpermute) so adjacent lanes share a row; retd rebalance kept
# speedup vs baseline: 1.0078x; 1.0034x over previous
.LBB0_300:
	s_andn2_b64 vcc, exec, s[2:3]
	s_cbranch_vccnz .LBB0_302
	v_mbcnt_lo_u32_b32 v251, -1, 0
	v_mbcnt_hi_u32_b32 v251, -1, v251
	v_and_b32_e32 v250, 15, v251
	v_sub_u32_e32 v170, v170, v250
	v_bfe_u32 v250, v251, 4, 2
	v_add_u32_e32 v170, v170, v250
	v_bfe_u32 v250, v251, 2, 2
	v_lshl_add_u32 v170, v250, 2, v170
	v_lshrrev_b32_e32 v250, 4, v251
	v_lshlrev_b32_e32 v250, 3, v250
	v_sub_u32_e32 v250, v200, v250
	v_and_b32_e32 v184, 3, v251
	v_lshl_add_u32 v250, v184, 3, v250
	v_lshlrev_b32_e32 v184, 4, v184
	v_bfe_u32 v185, v251, 4, 2
	v_add_u32_e32 v184, v184, v185
	v_bfe_u32 v185, v251, 2, 2
	v_lshl_add_u32 v184, v185, 2, v184
	v_lshlrev_b32_e32 v251, 2, v184
	s_cmpk_lt_i32 s16, 0x80
	s_movk_i32 s2, 0x3000
	s_cselect_b32 s2, 0x1800, s2
	s_cmp_gt_i32 s16, 63
	s_cselect_b32 s2, s2, 0
	s_lshl_b32 s2, s2, 2
	v_readlane_b32 s3, v255, 43
	v_lshl_or_b32 v130, s28, 8, v250
	s_add_u32 s2, s3, s2
	v_readlane_b32 s3, v255, 44
	v_ashrrev_i32_e32 v131, 31, v130
	s_addc_u32 s3, s3, 0
	v_lshlrev_b64 v[168:169], 2, v[130:131]
	v_lshl_add_u64 v[136:137], s[2:3], 0, v[168:169]
	global_load_dwordx4 v[132:135], v[136:137], off offset:16
	global_load_dwordx4 v[162:165], v[136:137], off
	global_load_dwordx4 v[172:175], v[136:137], off offset:528
	global_load_dwordx4 v[242:245], v[136:137], off offset:512
	v_mov_b32_e32 v143, v142
	v_readlane_b32 s2, v255, 26
	v_readlane_b32 s3, v255, 27
	v_ashrrev_i32_e32 v171, 31, v170
	v_lshlrev_b64 v[182:183], 12, v[170:171]
	v_lshl_add_u64 v[184:185], s[2:3], 0, v[168:169]
	v_lshl_add_u64 v[184:185], v[184:185], 0, v[182:183]
	v_lshl_add_u64 v[182:183], s[48:49], 0, v[182:183]
	v_lshl_add_u64 v[182:183], v[182:183], 0, v[168:169]
	global_load_dwordx4 v[202:205], v[184:185], off offset:528
	global_load_dwordx4 v[206:209], v[184:185], off offset:512
	global_load_dwordx4 v[210:213], v[184:185], off offset:16
	global_load_dwordx4 v[214:217], v[184:185], off
	s_mov_b64 s[2:3], 0x10000
	v_lshl_add_u64 v[168:169], v[184:185], 0, s[2:3]
	global_load_dwordx4 v[218:221], v[168:169], off offset:528
	global_load_dwordx4 v[222:225], v[168:169], off offset:512
	global_load_dwordx4 v[226:229], v[168:169], off offset:16
	global_load_dwordx4 v[230:233], v[168:169], off
	ds_bpermute_b32 v2, v251, v2
	ds_bpermute_b32 v3, v251, v3
	ds_bpermute_b32 v4, v251, v4
	ds_bpermute_b32 v5, v251, v5
	ds_bpermute_b32 v6, v251, v6
	ds_bpermute_b32 v7, v251, v7
	ds_bpermute_b32 v8, v251, v8
	ds_bpermute_b32 v9, v251, v9
	s_waitcnt lgkmcnt(4)
	ds_bpermute_b32 v10, v251, v10
	ds_bpermute_b32 v11, v251, v11
	ds_bpermute_b32 v12, v251, v12
	ds_bpermute_b32 v13, v251, v13
	ds_bpermute_b32 v14, v251, v14
	ds_bpermute_b32 v15, v251, v15
	ds_bpermute_b32 v16, v251, v16
	ds_bpermute_b32 v17, v251, v17
	s_waitcnt lgkmcnt(4)
	ds_bpermute_b32 v18, v251, v18
	ds_bpermute_b32 v19, v251, v19
	ds_bpermute_b32 v20, v251, v20
	ds_bpermute_b32 v21, v251, v21
	ds_bpermute_b32 v22, v251, v22
	ds_bpermute_b32 v23, v251, v23
	ds_bpermute_b32 v24, v251, v24
	ds_bpermute_b32 v25, v251, v25
	s_waitcnt lgkmcnt(4)
	ds_bpermute_b32 v26, v251, v26
	ds_bpermute_b32 v27, v251, v27
	ds_bpermute_b32 v28, v251, v28
	ds_bpermute_b32 v29, v251, v29
	ds_bpermute_b32 v30, v251, v30
	ds_bpermute_b32 v31, v251, v31
	ds_bpermute_b32 v32, v251, v32
	ds_bpermute_b32 v33, v251, v33
	s_waitcnt lgkmcnt(4)
	ds_bpermute_b32 v34, v251, v34
	ds_bpermute_b32 v35, v251, v35
	ds_bpermute_b32 v36, v251, v36
	ds_bpermute_b32 v37, v251, v37
	ds_bpermute_b32 v38, v251, v38
	ds_bpermute_b32 v39, v251, v39
	ds_bpermute_b32 v40, v251, v40
	ds_bpermute_b32 v41, v251, v41
	s_waitcnt lgkmcnt(4)
	ds_bpermute_b32 v42, v251, v42
	ds_bpermute_b32 v43, v251, v43
	ds_bpermute_b32 v44, v251, v44
	ds_bpermute_b32 v45, v251, v45
	ds_bpermute_b32 v46, v251, v46
	ds_bpermute_b32 v47, v251, v47
	ds_bpermute_b32 v48, v251, v48
	ds_bpermute_b32 v49, v251, v49
	s_waitcnt lgkmcnt(4)
	ds_bpermute_b32 v50, v251, v50
	ds_bpermute_b32 v51, v251, v51
	ds_bpermute_b32 v52, v251, v52
	ds_bpermute_b32 v53, v251, v53
	ds_bpermute_b32 v54, v251, v54
	ds_bpermute_b32 v55, v251, v55
	ds_bpermute_b32 v56, v251, v56
	ds_bpermute_b32 v57, v251, v57
	s_waitcnt lgkmcnt(4)
	ds_bpermute_b32 v58, v251, v58
	ds_bpermute_b32 v59, v251, v59
	ds_bpermute_b32 v60, v251, v60
	ds_bpermute_b32 v61, v251, v61
	ds_bpermute_b32 v62, v251, v62
	ds_bpermute_b32 v63, v251, v63
	ds_bpermute_b32 v64, v251, v64
	ds_bpermute_b32 v65, v251, v65
	s_waitcnt lgkmcnt(4)
	ds_bpermute_b32 v66, v251, v66
	ds_bpermute_b32 v67, v251, v67
	ds_bpermute_b32 v68, v251, v68
	ds_bpermute_b32 v69, v251, v69
	ds_bpermute_b32 v70, v251, v70
	ds_bpermute_b32 v71, v251, v71
	ds_bpermute_b32 v72, v251, v72
	ds_bpermute_b32 v73, v251, v73
	s_waitcnt lgkmcnt(4)
	ds_bpermute_b32 v74, v251, v74
	ds_bpermute_b32 v75, v251, v75
	ds_bpermute_b32 v76, v251, v76
	ds_bpermute_b32 v77, v251, v77
	ds_bpermute_b32 v78, v251, v78
	ds_bpermute_b32 v79, v251, v79
	ds_bpermute_b32 v80, v251, v80
	ds_bpermute_b32 v81, v251, v81
	s_waitcnt lgkmcnt(4)
	ds_bpermute_b32 v82, v251, v82
	ds_bpermute_b32 v83, v251, v83
	ds_bpermute_b32 v84, v251, v84
	ds_bpermute_b32 v85, v251, v85
	ds_bpermute_b32 v86, v251, v86
	ds_bpermute_b32 v87, v251, v87
	ds_bpermute_b32 v88, v251, v88
	ds_bpermute_b32 v89, v251, v89
	s_waitcnt lgkmcnt(4)
	ds_bpermute_b32 v90, v251, v90
	ds_bpermute_b32 v91, v251, v91
	ds_bpermute_b32 v92, v251, v92
	ds_bpermute_b32 v93, v251, v93
	ds_bpermute_b32 v94, v251, v94
	ds_bpermute_b32 v95, v251, v95
	ds_bpermute_b32 v96, v251, v96
	ds_bpermute_b32 v97, v251, v97
	s_waitcnt lgkmcnt(4)
	ds_bpermute_b32 v98, v251, v98
	ds_bpermute_b32 v99, v251, v99
	ds_bpermute_b32 v100, v251, v100
	ds_bpermute_b32 v101, v251, v101
	ds_bpermute_b32 v102, v251, v102
	ds_bpermute_b32 v103, v251, v103
	ds_bpermute_b32 v104, v251, v104
	ds_bpermute_b32 v105, v251, v105
	s_waitcnt lgkmcnt(4)
	ds_bpermute_b32 v106, v251, v106
	ds_bpermute_b32 v107, v251, v107
	ds_bpermute_b32 v108, v251, v108
	ds_bpermute_b32 v109, v251, v109
	ds_bpermute_b32 v110, v251, v110
	ds_bpermute_b32 v111, v251, v111
	ds_bpermute_b32 v112, v251, v112
	ds_bpermute_b32 v113, v251, v113
	s_waitcnt lgkmcnt(4)
	ds_bpermute_b32 v114, v251, v114
	ds_bpermute_b32 v115, v251, v115
	ds_bpermute_b32 v116, v251, v116
	ds_bpermute_b32 v117, v251, v117
	ds_bpermute_b32 v118, v251, v118
	ds_bpermute_b32 v119, v251, v119
	ds_bpermute_b32 v120, v251, v120
	ds_bpermute_b32 v121, v251, v121
	s_waitcnt lgkmcnt(4)
	ds_bpermute_b32 v122, v251, v122
	ds_bpermute_b32 v123, v251, v123
	ds_bpermute_b32 v124, v251, v124
	ds_bpermute_b32 v125, v251, v125
	ds_bpermute_b32 v126, v251, v126
	ds_bpermute_b32 v127, v251, v127
	ds_bpermute_b32 v128, v251, v128
	ds_bpermute_b32 v129, v251, v129
	s_waitcnt lgkmcnt(4)
	s_waitcnt vmcnt(10)
	v_pk_mul_f32 v[130:131], v[142:143], v[134:135]
	v_pk_mul_f32 v[160:161], v[142:143], v[164:165]
	v_pk_mul_f32 v[132:133], v[154:155], v[132:133]
	v_pk_mul_f32 v[162:163], v[154:155], v[162:163]
	s_waitcnt vmcnt(8)
	v_pk_mul_f32 v[164:165], v[142:143], v[244:245]
	v_pk_mul_f32 v[166:167], v[154:155], v[242:243]
	v_pk_mul_f32 v[134:135], v[142:143], v[174:175]
	v_pk_mul_f32 v[136:137], v[154:155], v[172:173]
	s_mov_b64 s[2:3], 0x20000
	v_lshl_add_u64 v[168:169], v[184:185], 0, s[2:3]
	global_load_dwordx4 v[234:237], v[168:169], off offset:528
	global_load_dwordx4 v[238:241], v[168:169], off offset:512
	global_load_dwordx4 v[242:245], v[168:169], off offset:16
	global_load_dwordx4 v[246:249], v[168:169], off
	s_waitcnt vmcnt(8) lgkmcnt(0)
	v_pk_fma_f32 v[114:115], v[114:115], v[136:137], v[202:203]
	v_pk_fma_f32 v[116:117], v[116:117], v[134:135], v[204:205]
	v_pk_fma_f32 v[118:119], v[118:119], v[166:167], v[206:207]
	v_pk_fma_f32 v[120:121], v[120:121], v[164:165], v[208:209]
	v_pk_fma_f32 v[122:123], v[122:123], v[132:133], v[210:211]
	v_pk_fma_f32 v[124:125], v[124:125], v[130:131], v[212:213]
	v_pk_fma_f32 v[126:127], v[126:127], v[162:163], v[214:215]
	v_pk_fma_f32 v[128:129], v[128:129], v[160:161], v[216:217]
	s_mov_b64 s[2:3], 0x30000
	v_lshl_add_u64 v[168:169], v[184:185], 0, s[2:3]
	global_load_dwordx4 v[202:205], v[168:169], off offset:528
	global_load_dwordx4 v[206:209], v[168:169], off offset:512
	global_load_dwordx4 v[210:213], v[168:169], off offset:16
	global_load_dwordx4 v[214:217], v[168:169], off
	global_store_dwordx4 v[182:183], v[114:117], off offset:528
	global_store_dwordx4 v[182:183], v[118:121], off offset:512
	global_store_dwordx4 v[182:183], v[122:125], off offset:16
	global_store_dwordx4 v[182:183], v[126:129], off
	s_mov_b64 s[2:3], 0x80000
	v_lshl_add_u64 v[168:169], v[184:185], 0, s[2:3]
	global_load_dwordx4 v[114:117], v[168:169], off offset:528
	global_load_dwordx4 v[118:121], v[168:169], off offset:512
	global_load_dwordx4 v[122:125], v[168:169], off offset:16
	global_load_dwordx4 v[126:129], v[168:169], off
	s_waitcnt vmcnt(16)
	v_pk_fma_f32 v[98:99], v[98:99], v[136:137], v[218:219]
	v_pk_fma_f32 v[100:101], v[100:101], v[134:135], v[220:221]
	v_pk_fma_f32 v[102:103], v[102:103], v[166:167], v[222:223]
	v_pk_fma_f32 v[104:105], v[104:105], v[164:165], v[224:225]
	v_pk_fma_f32 v[106:107], v[106:107], v[132:133], v[226:227]
	v_pk_fma_f32 v[108:109], v[108:109], v[130:131], v[228:229]
	v_pk_fma_f32 v[110:111], v[110:111], v[162:163], v[230:231]
	v_pk_fma_f32 v[112:113], v[112:113], v[160:161], v[232:233]
	s_mov_b64 s[2:3], 0x90000
	v_lshl_add_u64 v[168:169], v[184:185], 0, s[2:3]
	global_load_dwordx4 v[218:221], v[168:169], off offset:528
	global_load_dwordx4 v[222:225], v[168:169], off offset:512
	global_load_dwordx4 v[226:229], v[168:169], off offset:16
	global_load_dwordx4 v[230:233], v[168:169], off
	s_mov_b64 s[2:3], 0x10000
	v_lshl_add_u64 v[170:171], v[182:183], 0, s[2:3]
	global_store_dwordx4 v[170:171], v[98:101], off offset:528
	global_store_dwordx4 v[170:171], v[102:105], off offset:512
	global_store_dwordx4 v[170:171], v[106:109], off offset:16
	global_store_dwordx4 v[170:171], v[110:113], off
	s_mov_b64 s[2:3], 0xa0000
	v_lshl_add_u64 v[168:169], v[184:185], 0, s[2:3]
	global_load_dwordx4 v[98:101], v[168:169], off offset:528
	global_load_dwordx4 v[102:105], v[168:169], off offset:512
	global_load_dwordx4 v[106:109], v[168:169], off offset:16
	global_load_dwordx4 v[110:113], v[168:169], off
	s_waitcnt vmcnt(24)
	v_pk_fma_f32 v[82:83], v[82:83], v[136:137], v[234:235]
	v_pk_fma_f32 v[84:85], v[84:85], v[134:135], v[236:237]
	v_pk_fma_f32 v[86:87], v[86:87], v[166:167], v[238:239]
	v_pk_fma_f32 v[88:89], v[88:89], v[164:165], v[240:241]
	v_pk_fma_f32 v[90:91], v[90:91], v[132:133], v[242:243]
	v_pk_fma_f32 v[92:93], v[92:93], v[130:131], v[244:245]
	v_pk_fma_f32 v[94:95], v[94:95], v[162:163], v[246:247]
	v_pk_fma_f32 v[96:97], v[96:97], v[160:161], v[248:249]
	s_mov_b64 s[2:3], 0xb0000
	v_lshl_add_u64 v[168:169], v[184:185], 0, s[2:3]
	global_load_dwordx4 v[234:237], v[168:169], off offset:528
	global_load_dwordx4 v[238:241], v[168:169], off offset:512
	global_load_dwordx4 v[242:245], v[168:169], off offset:16
	global_load_dwordx4 v[246:249], v[168:169], off
	s_mov_b64 s[2:3], 0x20000
	v_lshl_add_u64 v[170:171], v[182:183], 0, s[2:3]
	global_store_dwordx4 v[170:171], v[82:85], off offset:528
	global_store_dwordx4 v[170:171], v[86:89], off offset:512
	global_store_dwordx4 v[170:171], v[90:93], off offset:16
	global_store_dwordx4 v[170:171], v[94:97], off
	s_waitcnt vmcnt(28)
	v_pk_fma_f32 v[66:67], v[66:67], v[136:137], v[202:203]
	v_pk_fma_f32 v[68:69], v[68:69], v[134:135], v[204:205]
	v_pk_fma_f32 v[70:71], v[70:71], v[166:167], v[206:207]
	v_pk_fma_f32 v[72:73], v[72:73], v[164:165], v[208:209]
	v_pk_fma_f32 v[74:75], v[74:75], v[132:133], v[210:211]
	v_pk_fma_f32 v[76:77], v[76:77], v[130:131], v[212:213]
	v_pk_fma_f32 v[78:79], v[78:79], v[162:163], v[214:215]
	v_pk_fma_f32 v[80:81], v[80:81], v[160:161], v[216:217]
	s_mov_b64 s[2:3], 0x30000
	v_lshl_add_u64 v[170:171], v[182:183], 0, s[2:3]
	global_store_dwordx4 v[170:171], v[66:69], off offset:528
	global_store_dwordx4 v[170:171], v[70:73], off offset:512
	global_store_dwordx4 v[170:171], v[74:77], off offset:16
	global_store_dwordx4 v[170:171], v[78:81], off
	s_waitcnt vmcnt(24)
	v_pk_fma_f32 v[50:51], v[50:51], v[136:137], v[114:115]
	v_pk_fma_f32 v[52:53], v[52:53], v[134:135], v[116:117]
	v_pk_fma_f32 v[54:55], v[54:55], v[166:167], v[118:119]
	v_pk_fma_f32 v[56:57], v[56:57], v[164:165], v[120:121]
	v_pk_fma_f32 v[58:59], v[58:59], v[132:133], v[122:123]
	v_pk_fma_f32 v[60:61], v[60:61], v[130:131], v[124:125]
	v_pk_fma_f32 v[62:63], v[62:63], v[162:163], v[126:127]
	v_pk_fma_f32 v[64:65], v[64:65], v[160:161], v[128:129]
	s_mov_b64 s[2:3], 0x80000
	v_lshl_add_u64 v[170:171], v[182:183], 0, s[2:3]
	global_store_dwordx4 v[170:171], v[50:53], off offset:528
	global_store_dwordx4 v[170:171], v[54:57], off offset:512
	global_store_dwordx4 v[170:171], v[58:61], off offset:16
	global_store_dwordx4 v[170:171], v[62:65], off
	s_waitcnt vmcnt(24)
	v_pk_fma_f32 v[34:35], v[34:35], v[136:137], v[218:219]
	v_pk_fma_f32 v[36:37], v[36:37], v[134:135], v[220:221]
	v_pk_fma_f32 v[38:39], v[38:39], v[166:167], v[222:223]
	v_pk_fma_f32 v[40:41], v[40:41], v[164:165], v[224:225]
	v_pk_fma_f32 v[42:43], v[42:43], v[132:133], v[226:227]
	v_pk_fma_f32 v[44:45], v[44:45], v[130:131], v[228:229]
	v_pk_fma_f32 v[46:47], v[46:47], v[162:163], v[230:231]
	v_pk_fma_f32 v[48:49], v[48:49], v[160:161], v[232:233]
	s_mov_b64 s[2:3], 0x90000
	v_lshl_add_u64 v[170:171], v[182:183], 0, s[2:3]
	global_store_dwordx4 v[170:171], v[34:37], off offset:528
	global_store_dwordx4 v[170:171], v[38:41], off offset:512
	global_store_dwordx4 v[170:171], v[42:45], off offset:16
	global_store_dwordx4 v[170:171], v[46:49], off
	s_waitcnt vmcnt(20)
	v_pk_fma_f32 v[18:19], v[18:19], v[136:137], v[98:99]
	v_pk_fma_f32 v[20:21], v[20:21], v[134:135], v[100:101]
	v_pk_fma_f32 v[22:23], v[22:23], v[166:167], v[102:103]
	v_pk_fma_f32 v[24:25], v[24:25], v[164:165], v[104:105]
	v_pk_fma_f32 v[26:27], v[26:27], v[132:133], v[106:107]
	v_pk_fma_f32 v[28:29], v[28:29], v[130:131], v[108:109]
	v_pk_fma_f32 v[30:31], v[30:31], v[162:163], v[110:111]
	v_pk_fma_f32 v[32:33], v[32:33], v[160:161], v[112:113]
	s_mov_b64 s[2:3], 0xa0000
	v_lshl_add_u64 v[170:171], v[182:183], 0, s[2:3]
	global_store_dwordx4 v[170:171], v[18:21], off offset:528
	global_store_dwordx4 v[170:171], v[22:25], off offset:512
	global_store_dwordx4 v[170:171], v[26:29], off offset:16
	global_store_dwordx4 v[170:171], v[30:33], off
	s_waitcnt vmcnt(20)
	v_pk_fma_f32 v[2:3], v[2:3], v[136:137], v[234:235]
	v_pk_fma_f32 v[4:5], v[4:5], v[134:135], v[236:237]
	v_pk_fma_f32 v[6:7], v[6:7], v[166:167], v[238:239]
	v_pk_fma_f32 v[8:9], v[8:9], v[164:165], v[240:241]
	v_pk_fma_f32 v[10:11], v[10:11], v[132:133], v[242:243]
	v_pk_fma_f32 v[12:13], v[12:13], v[130:131], v[244:245]
	v_pk_fma_f32 v[14:15], v[14:15], v[162:163], v[246:247]
	v_pk_fma_f32 v[16:17], v[16:17], v[160:161], v[248:249]
	s_mov_b64 s[2:3], 0xb0000
	v_lshl_add_u64 v[170:171], v[182:183], 0, s[2:3]
	global_store_dwordx4 v[170:171], v[2:5], off offset:528
	global_store_dwordx4 v[170:171], v[6:9], off offset:512
	global_store_dwordx4 v[170:171], v[10:13], off offset:16
	global_store_dwordx4 v[170:171], v[14:17], off
